# last layer: the two grid barriers between w_out, ffn_in and ffn_out GEMMs replaced by a four-workgroup same-XCD counter sync per row panel (guarded by an XCC-id placement check at kernel start, fallba
# speedup vs baseline: 1.0065x; 1.0004x over previous
_Z10hybrid_fwd4Args:
	s_mov_b32 s3, 0
	v_writelane_b32 v255, s3, 61
	s_mov_b32 s3, 0
	v_writelane_b32 v255, s3, 62
	s_load_dwordx4 s[52:55], s[0:1], 0x90
	s_mov_b32 s78, s2
	s_add_u32 s2, s0, 0xa0
	v_writelane_b32 v252, s0, 0
	s_addc_u32 s3, s1, 0
	v_and_b32_e32 v191, 0x3ff, v0
	v_writelane_b32 v252, s1, 1
	v_writelane_b32 v252, s2, 2
	v_cmp_gt_u32_e32 vcc, 64, v191
	s_nop 0
	v_writelane_b32 v252, s3, 3
	s_and_saveexec_b64 s[0:1], vcc
	v_lshl_add_u32 v1, v191, 2, 0
	v_add_u32_e32 v1, 0x24000, v1
	v_mov_b32_e32 v2, 0
	ds_write_b32 v1, v2
	s_or_b64 exec, exec, s[0:1]
	v_readlane_b32 s0, v252, 0
	v_readlane_b32 s1, v252, 1
	s_load_dwordx2 s[80:81], s[0:1], 0xa0
	s_waitcnt lgkmcnt(0)
	s_barrier
	s_getreg_b32 s0, hwreg(HW_REG_XCC_ID, 0, 4)
	s_and_b32 s4, s0, 15
	v_cmp_eq_u32_e64 s[2:3], 0, v191
	s_mov_b64 s[0:1], exec
	s_nop 0
	v_writelane_b32 v252, s2, 4
	s_nop 1
	v_writelane_b32 v252, s3, 5
	s_and_b64 s[2:3], s[0:1], s[2:3]
	s_mov_b64 exec, s[2:3]
	s_cbranch_execz .LBB0_5
	s_mov_b64 s[2:3], exec
	v_mbcnt_lo_u32_b32 v1, s2, 0
	v_mbcnt_hi_u32_b32 v1, s3, v1
	v_cmp_eq_u32_e32 vcc, 0, v1
	s_and_b64 s[6:7], exec, vcc
	s_mov_b64 exec, s[6:7]
	s_cbranch_execz .LBB0_5
	s_lshl_b32 s5, s4, 8
	s_bcnt1_i32_b64 s2, s[2:3]
	v_mov_b32_e32 v1, s5
	v_mov_b32_e32 v2, s2
	global_atomic_add v1, v2, s[52:53] offset:1024
	s_and_b32 s5, s78, 7
	s_cmp_eq_u32 s5, s4
	s_cbranch_scc1 .Lxcc_ok
	v_mov_b32_e32 v1, 0x16e00
	s_nop 0
	global_atomic_add v1, v2, s[52:53]
.Lxcc_ok:
.LBB0_5:
	s_or_b64 exec, exec, s[0:1]
	s_cmp_ge_i32 s54, s55
	s_cbranch_scc0 .LBB0_6
	s_getpc_b64 s[98:99]

.Ll4_b:
	s_add_i32 s54, s54, 1
	s_cmp_eq_u32 s54, 15
	s_cselect_b32 s54, s55, s54
	v_readlane_b32 s26, v254, 21
	v_readlane_b32 s36, v254, 25
	v_readlane_b32 s40, v254, 29
	s_cmp_ge_i32 s54, s55
	v_readlane_b32 s27, v254, 22
	v_readlane_b32 s37, v254, 26
	v_readlane_b32 s41, v254, 30
	s_cbranch_scc1 .Lskip_seam
	v_readlane_b32 s0, v255, 61
	s_nop 3
	s_cmp_eq_u32 s0, 1
	s_cbranch_scc1 .LBB0_1379
	s_cmp_eq_u32 s54, 12
	s_cbranch_scc1 .Lpsync
	s_cmp_eq_u32 s54, 14
	s_cbranch_scc1 .Lpsync
	s_cmp_eq_u32 s54, 6
	s_cbranch_scc1 .Lskip_seam
	s_cmp_eq_u32 s54, 9
	s_cbranch_scc0 .LBB0_1379

.Lpsync:
	v_readlane_b32 s0, v254, 10
	v_readlane_b32 s1, v254, 11
	s_nop 3
	s_add_u32 s2, s0, 0x16e00
	s_addc_u32 s3, s1, 0
	s_mov_b64 vcc, exec
	s_mov_b32 exec_lo, 0
	s_brev_b32 exec_hi, 1
	global_load_dword v255, v1, s[2:3] sc1
	s_waitcnt vmcnt(0)
	v_readlane_b32 s2, v255, 63
	s_mov_b64 exec, vcc
	s_nop 3
	s_cmp_lg_u32 s2, 0
	s_cbranch_scc1 .LBB0_1379
	s_waitcnt vmcnt(0)
	s_barrier
	v_readfirstlane_b32 s2, v191
	s_nop 3
	s_cmp_lt_u32 s2, 64
	s_cbranch_scc0 .Lpsync_bar
	s_and_b32 s2, s78, 7
	s_lshl_b32 s2, s2, 8
	s_bfe_u32 s3, s78, 0x30003
	s_lshl_b32 s3, s3, 2
	s_add_i32 s2, s2, s3
	s_add_i32 s2, s2, 0x16f00
	s_add_u32 s0, s0, s2
	s_addc_u32 s1, s1, 0
	s_cmp_eq_u32 s54, 12
	s_cselect_b32 s3, 4, 8
	s_mov_b64 vcc, exec
	s_mov_b32 exec_lo, 0
	s_brev_b32 exec_hi, 1
	global_atomic_add v1, v220, s[0:1]
	s_mov_b32 s2, 0
.Lpsync_spin:
	global_load_dword v255, v1, s[0:1] sc1
	s_waitcnt vmcnt(0)
	v_readlane_b32 s4, v255, 63
	s_nop 3
	s_cmp_ge_u32 s4, s3
	s_cbranch_scc1 .Lpsync_got
	s_sleep 1
	s_add_u32 s2, s2, 1
	s_cmp_lt_u32 s2, 0x1000
	s_cbranch_scc1 .Lpsync_spin

.Lpsync_bar:
	s_barrier
	s_branch .Lskip_seam
